# GEMM epilogue dwordx4 stores marked sc1 (write-through) so the grid barrier's L2 writeback finds less dirty data
# baseline (speedup 1.0000x reference)
; __device__ __forceinline__ unsigned cvt_pk_bf16(float lo, float hi) { unsigned r; asm volatile("v_cvt_pk_bf16_f32 %0, %1, %2" : "=v"(r) : "v"(lo), "v"(hi)); return r; }
; __device__ __forceinline__ float silu_f(float g) { return g * __builtin_amdgcn_rcpf(1.f + __expf(-g)); }
;     __device__ __forceinline__ void operator()(const f32x4 (&acc)[2][2][4][2], const Unit& u, int wr, int wc, int fr, int fq) const {
;         const int row0 = phys_tile(u.pm, skipctx) * BM + wr * 64 + fr, col0 = u.pn * HALF + wc * 32 + 8 * fq;
; #pragma unroll
;         for (int ai = 0; ai < 2; ++ai)
; #pragma unroll
;             for (int m = 0; m < 4; ++m) { bf16_t* rowp = O + (size_t)(row0 + ai * HALF + m * 16) * DFF + col0;
;                 float r[8];
; #pragma unroll
;                 for (int n = 0; n < 2; ++n)
; #pragma unroll
;                     for (int e = 0; e < 4; ++e) r[n * 4 + e] = silu_f(acc[ai][0][m][n][e]) * acc[ai][1][m][n][e];
;                 u32x4 w; w.x = cvt_pk_bf16(r[0], r[1]); w.y = cvt_pk_bf16(r[2], r[3]); w.z = cvt_pk_bf16(r[4], r[5]); w.w = cvt_pk_bf16(r[6], r[7]);
;                 *(u32x4*)rowp = w; }
;     }
.LBB0_201:
	v_mul_f32_e32 v147, 0xbfb8aa3b, v126
	v_exp_f32_e32 v147, v147
	s_lshr_b32 s5, s4, 4
	s_add_i32 s5, s4, s5
	s_add_i32 s5, s5, 1
	v_add_f32_e32 v147, 1.0, v147
	v_rcp_f32_e32 v147, v147
	s_and_b64 s[6:7], s[12:13], exec
	s_cselect_b32 s4, s5, s4
	v_lshl_or_b32 v148, s20, 7, v144
	v_mul_f32_e32 v126, v126, v147
	v_mul_f32_e32 v122, v126, v122
	v_mul_f32_e32 v126, 0xbfb8aa3b, v127
	v_exp_f32_e32 v126, v126
	v_lshl_add_u32 v146, s4, 8, v142
	v_ashrrev_i32_e32 v149, 31, v148
	v_mov_b64_e32 v[140:141], s[44:45]
	v_add_f32_e32 v126, 1.0, v126
	v_rcp_f32_e32 v126, v126
	v_mad_i64_i32 v[150:151], s[4:5], v146, s56, v[140:141]
	s_mov_b64 s[14:15], -1
	v_mul_f32_e32 v126, v127, v126
	v_mul_f32_e32 v123, v126, v123
	v_mul_f32_e32 v126, 0xbfb8aa3b, v128
	v_exp_f32_e32 v126, v126
	s_andn2_b64 vcc, exec, s[38:39]
	v_add_f32_e32 v126, 1.0, v126
	v_rcp_f32_e32 v126, v126
	s_nop 0
	v_mul_f32_e32 v126, v128, v126
	v_mul_f32_e32 v124, v126, v124
	v_mul_f32_e32 v126, 0xbfb8aa3b, v129
	v_exp_f32_e32 v126, v126
	s_nop 0
	v_add_f32_e32 v126, 1.0, v126
	v_rcp_f32_e32 v126, v126
	s_nop 0
	v_mul_f32_e32 v126, v129, v126
	v_mul_f32_e32 v125, v126, v125
	v_mul_f32_e32 v126, 0xbfb8aa3b, v118
	v_exp_f32_e32 v126, v126
	s_nop 0
	v_add_f32_e32 v126, 1.0, v126
	v_rcp_f32_e32 v126, v126
	s_nop 0
	v_mul_f32_e32 v118, v118, v126
	v_mul_f32_e32 v118, v118, v114
	v_mul_f32_e32 v114, 0xbfb8aa3b, v119
	v_exp_f32_e32 v114, v114
	s_nop 0
	v_add_f32_e32 v114, 1.0, v114
	v_rcp_f32_e32 v114, v114
	s_nop 0
	v_mul_f32_e32 v114, v119, v114
	v_mul_f32_e32 v119, v114, v115
	v_mul_f32_e32 v114, 0xbfb8aa3b, v120
	v_exp_f32_e32 v114, v114
	s_nop 0
	v_add_f32_e32 v114, 1.0, v114
	v_rcp_f32_e32 v114, v114
	s_nop 0
	v_mul_f32_e32 v114, v120, v114
	v_mul_f32_e32 v126, v114, v116
	v_mul_f32_e32 v114, 0xbfb8aa3b, v121
	v_exp_f32_e32 v114, v114
	v_cvt_pk_bf16_f32 v116, v122, v123
	s_nop 0
	v_add_f32_e32 v114, 1.0, v114
	v_rcp_f32_e32 v114, v114
	s_nop 0
	v_mul_f32_e32 v114, v121, v114
	v_mul_f32_e32 v127, v114, v117
	v_lshlrev_b64 v[114:115], 1, v[148:149]
	v_lshl_add_u64 v[120:121], v[150:151], 0, v[114:115]
	v_cvt_pk_bf16_f32 v117, v124, v125
	v_cvt_pk_bf16_f32 v118, v118, v119
	v_cvt_pk_bf16_f32 v119, v126, v127
	global_store_dwordx4 v[120:121], v[116:119], off sc1
	s_nop 1
	v_mul_f32_e32 v118, 0xbfb8aa3b, v110
	v_exp_f32_e32 v118, v118
	v_or_b32_e32 v116, 16, v146
	v_mad_i64_i32 v[116:117], s[4:5], v116, s56, v[140:141]
	v_add_f32_e32 v118, 1.0, v118
	v_rcp_f32_e32 v118, v118
	s_nop 0
	v_mul_f32_e32 v110, v110, v118
	v_mul_f32_e32 v106, v110, v106
	v_mul_f32_e32 v110, 0xbfb8aa3b, v111
	v_exp_f32_e32 v110, v110
	s_nop 0
	v_add_f32_e32 v110, 1.0, v110
	v_rcp_f32_e32 v110, v110
	s_nop 0
	v_mul_f32_e32 v110, v111, v110
	v_mul_f32_e32 v107, v110, v107
	v_mul_f32_e32 v110, 0xbfb8aa3b, v112
	v_exp_f32_e32 v110, v110
	s_nop 0
	v_add_f32_e32 v110, 1.0, v110
	v_rcp_f32_e32 v110, v110
	s_nop 0
	v_mul_f32_e32 v110, v112, v110
	v_mul_f32_e32 v108, v110, v108
	v_mul_f32_e32 v110, 0xbfb8aa3b, v113
	v_exp_f32_e32 v110, v110
	s_nop 0
	v_add_f32_e32 v110, 1.0, v110
	v_rcp_f32_e32 v110, v110
	s_nop 0
	v_mul_f32_e32 v110, v113, v110
	v_mul_f32_e32 v109, v110, v109
	v_mul_f32_e32 v110, 0xbfb8aa3b, v102
	v_exp_f32_e32 v110, v110
	s_nop 0
	v_add_f32_e32 v110, 1.0, v110
	v_rcp_f32_e32 v110, v110
	s_nop 0
	v_mul_f32_e32 v102, v102, v110
	v_mul_f32_e32 v110, v102, v98
	v_mul_f32_e32 v98, 0xbfb8aa3b, v103
	v_exp_f32_e32 v98, v98
	s_nop 0
	v_add_f32_e32 v98, 1.0, v98
	v_rcp_f32_e32 v98, v98
	s_nop 0
	v_mul_f32_e32 v98, v103, v98
	v_mul_f32_e32 v111, v98, v99
	v_mul_f32_e32 v98, 0xbfb8aa3b, v104
	v_exp_f32_e32 v98, v98
	v_lshl_add_u64 v[102:103], v[116:117], 0, v[114:115]
	v_add_f32_e32 v98, 1.0, v98
	v_rcp_f32_e32 v98, v98
	s_nop 0
	v_mul_f32_e32 v98, v104, v98
	v_mul_f32_e32 v104, v98, v100
	v_mul_f32_e32 v98, 0xbfb8aa3b, v105
	v_exp_f32_e32 v98, v98
	s_nop 0
	v_add_f32_e32 v98, 1.0, v98
	v_rcp_f32_e32 v98, v98
	s_nop 0
	v_mul_f32_e32 v98, v105, v98
	v_mul_f32_e32 v101, v98, v101
	v_cvt_pk_bf16_f32 v98, v106, v107
	v_cvt_pk_bf16_f32 v99, v108, v109
	v_cvt_pk_bf16_f32 v100, v110, v111
	v_cvt_pk_bf16_f32 v101, v104, v101
	global_store_dwordx4 v[102:103], v[98:101], off sc1
	s_nop 1
	v_mul_f32_e32 v100, 0xbfb8aa3b, v94
	v_exp_f32_e32 v100, v100
	v_or_b32_e32 v98, 32, v146
	v_mad_i64_i32 v[98:99], s[4:5], v98, s56, v[140:141]
	v_add_f32_e32 v100, 1.0, v100
	v_rcp_f32_e32 v100, v100
	s_nop 0
	v_mul_f32_e32 v94, v94, v100
	v_mul_f32_e32 v90, v94, v90
	v_mul_f32_e32 v94, 0xbfb8aa3b, v95
	v_exp_f32_e32 v94, v94
	s_nop 0
	v_add_f32_e32 v94, 1.0, v94
	v_rcp_f32_e32 v94, v94
	s_nop 0
	v_mul_f32_e32 v94, v95, v94
	v_mul_f32_e32 v91, v94, v91
	v_mul_f32_e32 v94, 0xbfb8aa3b, v96
	v_exp_f32_e32 v94, v94
	s_nop 0
	v_add_f32_e32 v94, 1.0, v94
	v_rcp_f32_e32 v94, v94
	s_nop 0
	v_mul_f32_e32 v94, v96, v94
	v_mul_f32_e32 v92, v94, v92
	v_mul_f32_e32 v94, 0xbfb8aa3b, v97
	v_exp_f32_e32 v94, v94
	s_nop 0
	v_add_f32_e32 v94, 1.0, v94
	v_rcp_f32_e32 v94, v94
	s_nop 0
	v_mul_f32_e32 v94, v97, v94
	v_mul_f32_e32 v93, v94, v93
	v_mul_f32_e32 v94, 0xbfb8aa3b, v86
	v_exp_f32_e32 v94, v94
	s_nop 0
	v_add_f32_e32 v94, 1.0, v94
	v_rcp_f32_e32 v94, v94
	s_nop 0
	v_mul_f32_e32 v86, v86, v94
	v_mul_f32_e32 v94, v86, v82
	v_mul_f32_e32 v82, 0xbfb8aa3b, v87
	v_exp_f32_e32 v82, v82
	s_nop 0
	v_add_f32_e32 v82, 1.0, v82
	v_rcp_f32_e32 v82, v82
	s_nop 0
	v_mul_f32_e32 v82, v87, v82
	v_mul_f32_e32 v95, v82, v83
	v_mul_f32_e32 v82, 0xbfb8aa3b, v88
	v_exp_f32_e32 v82, v82
	v_lshl_add_u64 v[86:87], v[98:99], 0, v[114:115]
	v_add_f32_e32 v82, 1.0, v82
	v_rcp_f32_e32 v82, v82
	s_nop 0
	v_mul_f32_e32 v82, v88, v82
	v_mul_f32_e32 v88, v82, v84
; __device__ __forceinline__ unsigned cvt_pk_bf16(float lo, float hi) { unsigned r; asm volatile("v_cvt_pk_bf16_f32 %0, %1, %2" : "=v"(r) : "v"(lo), "v"(hi)); return r; }
; __device__ __forceinline__ float silu_f(float g) { return g * __builtin_amdgcn_rcpf(1.f + __expf(-g)); }
;     __device__ __forceinline__ void operator()(const f32x4 (&acc)[2][2][4][2], const Unit& u, int wr, int wc, int fr, int fq) const {
;         const int row0 = phys_tile(u.pm, skipctx) * BM + wr * 64 + fr, col0 = u.pn * HALF + wc * 32 + 8 * fq;
; #pragma unroll
;         for (int ai = 0; ai < 2; ++ai)
; #pragma unroll
;             for (int m = 0; m < 4; ++m) { bf16_t* rowp = O + (size_t)(row0 + ai * HALF + m * 16) * DFF + col0;
;                 float r[8];
; #pragma unroll
;                 for (int n = 0; n < 2; ++n)
; #pragma unroll
;                     for (int e = 0; e < 4; ++e) r[n * 4 + e] = silu_f(acc[ai][0][m][n][e]) * acc[ai][1][m][n][e];
;                 u32x4 w; w.x = cvt_pk_bf16(r[0], r[1]); w.y = cvt_pk_bf16(r[2], r[3]); w.z = cvt_pk_bf16(r[4], r[5]); w.w = cvt_pk_bf16(r[6], r[7]);
;                 *(u32x4*)rowp = w; }
;     }
	v_mul_f32_e32 v82, 0xbfb8aa3b, v89
	v_exp_f32_e32 v82, v82
	s_nop 0
	v_add_f32_e32 v82, 1.0, v82
	v_rcp_f32_e32 v82, v82
	s_nop 0
	v_mul_f32_e32 v82, v89, v82
	v_mul_f32_e32 v85, v82, v85
	v_cvt_pk_bf16_f32 v82, v90, v91
	v_cvt_pk_bf16_f32 v83, v92, v93
	v_cvt_pk_bf16_f32 v84, v94, v95
	v_cvt_pk_bf16_f32 v85, v88, v85
	global_store_dwordx4 v[86:87], v[82:85], off sc1
	s_nop 1
	v_mul_f32_e32 v84, 0xbfb8aa3b, v78
	v_exp_f32_e32 v84, v84
	v_or_b32_e32 v82, 48, v146
	v_mad_i64_i32 v[82:83], s[4:5], v82, s56, v[140:141]
	v_add_f32_e32 v84, 1.0, v84
	v_rcp_f32_e32 v84, v84
	s_nop 0
	v_mul_f32_e32 v78, v78, v84
	v_mul_f32_e32 v74, v78, v74
	v_mul_f32_e32 v78, 0xbfb8aa3b, v79
	v_exp_f32_e32 v78, v78
	s_nop 0
	v_add_f32_e32 v78, 1.0, v78
	v_rcp_f32_e32 v78, v78
	s_nop 0
	v_mul_f32_e32 v78, v79, v78
	v_mul_f32_e32 v75, v78, v75
	v_mul_f32_e32 v78, 0xbfb8aa3b, v80
	v_exp_f32_e32 v78, v78
	s_nop 0
	v_add_f32_e32 v78, 1.0, v78
	v_rcp_f32_e32 v78, v78
	s_nop 0
	v_mul_f32_e32 v78, v80, v78
	v_mul_f32_e32 v76, v78, v76
	v_mul_f32_e32 v78, 0xbfb8aa3b, v81
	v_exp_f32_e32 v78, v78
	s_nop 0
	v_add_f32_e32 v78, 1.0, v78
	v_rcp_f32_e32 v78, v78
	s_nop 0
	v_mul_f32_e32 v78, v81, v78
	v_mul_f32_e32 v77, v78, v77
	v_mul_f32_e32 v78, 0xbfb8aa3b, v70
	v_exp_f32_e32 v78, v78
	s_nop 0
	v_add_f32_e32 v78, 1.0, v78
	v_rcp_f32_e32 v78, v78
	s_nop 0
	v_mul_f32_e32 v70, v70, v78
	v_mul_f32_e32 v78, v70, v66
	v_mul_f32_e32 v66, 0xbfb8aa3b, v71
	v_exp_f32_e32 v66, v66
	s_nop 0
	v_add_f32_e32 v66, 1.0, v66
	v_rcp_f32_e32 v66, v66
	s_nop 0
	v_mul_f32_e32 v66, v71, v66
	v_mul_f32_e32 v79, v66, v67
	v_mul_f32_e32 v66, 0xbfb8aa3b, v72
	v_exp_f32_e32 v66, v66
	v_lshl_add_u64 v[70:71], v[82:83], 0, v[114:115]
	v_add_f32_e32 v66, 1.0, v66
	v_rcp_f32_e32 v66, v66
	s_nop 0
	v_mul_f32_e32 v66, v72, v66
	v_mul_f32_e32 v72, v66, v68
	v_mul_f32_e32 v66, 0xbfb8aa3b, v73
	v_exp_f32_e32 v66, v66
	s_nop 0
	v_add_f32_e32 v66, 1.0, v66
	v_rcp_f32_e32 v66, v66
	s_nop 0
	v_mul_f32_e32 v66, v73, v66
	v_mul_f32_e32 v69, v66, v69
	v_cvt_pk_bf16_f32 v66, v74, v75
	v_cvt_pk_bf16_f32 v67, v76, v77
	v_cvt_pk_bf16_f32 v68, v78, v79
	v_cvt_pk_bf16_f32 v69, v72, v69
	global_store_dwordx4 v[70:71], v[66:69], off sc1
	s_nop 1
	v_mul_f32_e32 v68, 0xbfb8aa3b, v62
	v_exp_f32_e32 v68, v68
	v_add_u32_e32 v66, 0x80, v146
	v_mad_i64_i32 v[66:67], s[4:5], v66, s56, v[140:141]
	v_add_f32_e32 v68, 1.0, v68
	v_rcp_f32_e32 v68, v68
	s_nop 0
	v_mul_f32_e32 v62, v62, v68
	v_mul_f32_e32 v58, v62, v58
	v_mul_f32_e32 v62, 0xbfb8aa3b, v63
	v_exp_f32_e32 v62, v62
	s_nop 0
	v_add_f32_e32 v62, 1.0, v62
	v_rcp_f32_e32 v62, v62
	s_nop 0
	v_mul_f32_e32 v62, v63, v62
	v_mul_f32_e32 v59, v62, v59
	v_mul_f32_e32 v62, 0xbfb8aa3b, v64
	v_exp_f32_e32 v62, v62
	s_nop 0
	v_add_f32_e32 v62, 1.0, v62
	v_rcp_f32_e32 v62, v62
	s_nop 0
	v_mul_f32_e32 v62, v64, v62
	v_mul_f32_e32 v60, v62, v60
	v_mul_f32_e32 v62, 0xbfb8aa3b, v65
	v_exp_f32_e32 v62, v62
	s_nop 0
	v_add_f32_e32 v62, 1.0, v62
	v_rcp_f32_e32 v62, v62
	s_nop 0
	v_mul_f32_e32 v62, v65, v62
	v_mul_f32_e32 v61, v62, v61
	v_mul_f32_e32 v62, 0xbfb8aa3b, v54
	v_exp_f32_e32 v62, v62
	s_nop 0
	v_add_f32_e32 v62, 1.0, v62
	v_rcp_f32_e32 v62, v62
	s_nop 0
	v_mul_f32_e32 v54, v54, v62
	v_mul_f32_e32 v62, v54, v50
	v_mul_f32_e32 v50, 0xbfb8aa3b, v55
	v_exp_f32_e32 v50, v50
	s_nop 0
	v_add_f32_e32 v50, 1.0, v50
	v_rcp_f32_e32 v50, v50
	s_nop 0
	v_mul_f32_e32 v50, v55, v50
	v_mul_f32_e32 v63, v50, v51
	v_mul_f32_e32 v50, 0xbfb8aa3b, v56
	v_exp_f32_e32 v50, v50
	v_lshl_add_u64 v[54:55], v[66:67], 0, v[114:115]
	v_add_f32_e32 v50, 1.0, v50
	v_rcp_f32_e32 v50, v50
	s_nop 0
	v_mul_f32_e32 v50, v56, v50
	v_mul_f32_e32 v56, v50, v52
	v_mul_f32_e32 v50, 0xbfb8aa3b, v57
	v_exp_f32_e32 v50, v50
	s_nop 0
	v_add_f32_e32 v50, 1.0, v50
	v_rcp_f32_e32 v50, v50
	s_nop 0
	v_mul_f32_e32 v50, v57, v50
	v_mul_f32_e32 v53, v50, v53
	v_cvt_pk_bf16_f32 v50, v58, v59
	v_cvt_pk_bf16_f32 v51, v60, v61
	v_cvt_pk_bf16_f32 v52, v62, v63
	v_cvt_pk_bf16_f32 v53, v56, v53
	global_store_dwordx4 v[54:55], v[50:53], off sc1
	s_nop 1
	v_mul_f32_e32 v52, 0xbfb8aa3b, v46
	v_exp_f32_e32 v52, v52
	v_add_u32_e32 v50, 0x90, v146
	v_mad_i64_i32 v[50:51], s[4:5], v50, s56, v[140:141]
	v_add_f32_e32 v52, 1.0, v52
	v_rcp_f32_e32 v52, v52
	s_nop 0
	v_mul_f32_e32 v46, v46, v52
	v_mul_f32_e32 v42, v46, v42
	v_mul_f32_e32 v46, 0xbfb8aa3b, v47
	v_exp_f32_e32 v46, v46
	s_nop 0
	v_add_f32_e32 v46, 1.0, v46
	v_rcp_f32_e32 v46, v46
	s_nop 0
	v_mul_f32_e32 v46, v47, v46
	v_mul_f32_e32 v43, v46, v43
	v_mul_f32_e32 v46, 0xbfb8aa3b, v48
	v_exp_f32_e32 v46, v46
	s_nop 0
	v_add_f32_e32 v46, 1.0, v46
	v_rcp_f32_e32 v46, v46
	s_nop 0
	v_mul_f32_e32 v46, v48, v46
	v_mul_f32_e32 v44, v46, v44
	v_mul_f32_e32 v46, 0xbfb8aa3b, v49
	v_exp_f32_e32 v46, v46
	s_nop 0
	v_add_f32_e32 v46, 1.0, v46
; __device__ __forceinline__ unsigned cvt_pk_bf16(float lo, float hi) { unsigned r; asm volatile("v_cvt_pk_bf16_f32 %0, %1, %2" : "=v"(r) : "v"(lo), "v"(hi)); return r; }
; __device__ __forceinline__ float silu_f(float g) { return g * __builtin_amdgcn_rcpf(1.f + __expf(-g)); }
; #define PG8_BAR __builtin_amdgcn_s_barrier()
;     __device__ __forceinline__ void operator()(const f32x4 (&acc)[2][2][4][2], const Unit& u, int wr, int wc, int fr, int fq) const {
;         const int row0 = phys_tile(u.pm, skipctx) * BM + wr * 64 + fr, col0 = u.pn * HALF + wc * 32 + 8 * fq;
; #pragma unroll
;         for (int ai = 0; ai < 2; ++ai)
; #pragma unroll
;             for (int m = 0; m < 4; ++m) { bf16_t* rowp = O + (size_t)(row0 + ai * HALF + m * 16) * DFF + col0;
;                 float r[8];
; #pragma unroll
;                 for (int n = 0; n < 2; ++n)
; #pragma unroll
;                     for (int e = 0; e < 4; ++e) r[n * 4 + e] = silu_f(acc[ai][0][m][n][e]) * acc[ai][1][m][n][e];
;                 u32x4 w; w.x = cvt_pk_bf16(r[0], r[1]); w.y = cvt_pk_bf16(r[2], r[3]); w.z = cvt_pk_bf16(r[4], r[5]); w.w = cvt_pk_bf16(r[6], r[7]);
;                 *(u32x4*)rowp = w; }
;     }
; template <class Epi>
; __device__ __forceinline__ void gemm_phase(LAS unsigned char* lds, const Gemm g, const StaticOrder& S, const Epi& E) {
;     ...
;         if (wr == 0) PG8_BAR;
;         E(acc, cur, wr, wc, fr, fq);
;         if (!has_next) break;
; #pragma unroll
;         for (int a = 0; a < 2; ++a)
; #pragma unroll
;             for (int b = 0; b < 2; ++b)
; #pragma unroll
;                 for (int m = 0; m < 4; ++m)
; #pragma unroll
;                     for (int n = 0; n < 2; ++n) acc[a][b][m][n] = (f32x4){0.f, 0.f, 0.f, 0.f};
;         cur = nxt; cA = nA; cB = nB; ++ui;
;         if (wr == 1) PG8_BAR;
	v_rcp_f32_e32 v46, v46
	s_nop 0
	v_mul_f32_e32 v46, v49, v46
	v_mul_f32_e32 v45, v46, v45
	v_mul_f32_e32 v46, 0xbfb8aa3b, v38
	v_exp_f32_e32 v46, v46
	s_nop 0
	v_add_f32_e32 v46, 1.0, v46
	v_rcp_f32_e32 v46, v46
	s_nop 0
	v_mul_f32_e32 v38, v38, v46
	v_mul_f32_e32 v46, v38, v34
	v_mul_f32_e32 v34, 0xbfb8aa3b, v39
	v_exp_f32_e32 v34, v34
	s_nop 0
	v_add_f32_e32 v34, 1.0, v34
	v_rcp_f32_e32 v34, v34
	s_nop 0
	v_mul_f32_e32 v34, v39, v34
	v_mul_f32_e32 v47, v34, v35
	v_mul_f32_e32 v34, 0xbfb8aa3b, v40
	v_exp_f32_e32 v34, v34
	v_lshl_add_u64 v[38:39], v[50:51], 0, v[114:115]
	v_add_f32_e32 v34, 1.0, v34
	v_rcp_f32_e32 v34, v34
	s_nop 0
	v_mul_f32_e32 v34, v40, v34
	v_mul_f32_e32 v40, v34, v36
	v_mul_f32_e32 v34, 0xbfb8aa3b, v41
	v_exp_f32_e32 v34, v34
	s_nop 0
	v_add_f32_e32 v34, 1.0, v34
	v_rcp_f32_e32 v34, v34
	s_nop 0
	v_mul_f32_e32 v34, v41, v34
	v_mul_f32_e32 v37, v34, v37
	v_cvt_pk_bf16_f32 v34, v42, v43
	v_cvt_pk_bf16_f32 v35, v44, v45
	v_cvt_pk_bf16_f32 v36, v46, v47
	v_cvt_pk_bf16_f32 v37, v40, v37
	global_store_dwordx4 v[38:39], v[34:37], off sc1
	s_nop 1
	v_mul_f32_e32 v36, 0xbfb8aa3b, v30
	v_exp_f32_e32 v36, v36
	v_add_u32_e32 v34, 0xa0, v146
	v_mad_i64_i32 v[34:35], s[4:5], v34, s56, v[140:141]
	v_add_f32_e32 v36, 1.0, v36
	v_rcp_f32_e32 v36, v36
	s_nop 0
	v_mul_f32_e32 v30, v30, v36
	v_mul_f32_e32 v26, v30, v26
	v_mul_f32_e32 v30, 0xbfb8aa3b, v31
	v_exp_f32_e32 v30, v30
	s_nop 0
	v_add_f32_e32 v30, 1.0, v30
	v_rcp_f32_e32 v30, v30
	s_nop 0
	v_mul_f32_e32 v30, v31, v30
	v_mul_f32_e32 v27, v30, v27
	v_mul_f32_e32 v30, 0xbfb8aa3b, v32
	v_exp_f32_e32 v30, v30
	s_nop 0
	v_add_f32_e32 v30, 1.0, v30
	v_rcp_f32_e32 v30, v30
	s_nop 0
	v_mul_f32_e32 v30, v32, v30
	v_mul_f32_e32 v28, v30, v28
	v_mul_f32_e32 v30, 0xbfb8aa3b, v33
	v_exp_f32_e32 v30, v30
	s_nop 0
	v_add_f32_e32 v30, 1.0, v30
	v_rcp_f32_e32 v30, v30
	s_nop 0
	v_mul_f32_e32 v30, v33, v30
	v_mul_f32_e32 v29, v30, v29
	v_mul_f32_e32 v30, 0xbfb8aa3b, v22
	v_exp_f32_e32 v30, v30
	s_nop 0
	v_add_f32_e32 v30, 1.0, v30
	v_rcp_f32_e32 v30, v30
	s_nop 0
	v_mul_f32_e32 v22, v22, v30
	v_mul_f32_e32 v30, v22, v18
	v_mul_f32_e32 v18, 0xbfb8aa3b, v23
	v_exp_f32_e32 v18, v18
	s_nop 0
	v_add_f32_e32 v18, 1.0, v18
	v_rcp_f32_e32 v18, v18
	s_nop 0
	v_mul_f32_e32 v18, v23, v18
	v_mul_f32_e32 v31, v18, v19
	v_mul_f32_e32 v18, 0xbfb8aa3b, v24
	v_exp_f32_e32 v18, v18
	v_lshl_add_u64 v[22:23], v[34:35], 0, v[114:115]
	v_add_f32_e32 v18, 1.0, v18
	v_rcp_f32_e32 v18, v18
	s_nop 0
	v_mul_f32_e32 v18, v24, v18
	v_mul_f32_e32 v24, v18, v20
	v_mul_f32_e32 v18, 0xbfb8aa3b, v25
	v_exp_f32_e32 v18, v18
	s_nop 0
	v_add_f32_e32 v18, 1.0, v18
	v_rcp_f32_e32 v18, v18
	s_nop 0
	v_mul_f32_e32 v18, v25, v18
	v_mul_f32_e32 v21, v18, v21
	v_cvt_pk_bf16_f32 v18, v26, v27
	v_cvt_pk_bf16_f32 v19, v28, v29
	v_cvt_pk_bf16_f32 v20, v30, v31
	v_cvt_pk_bf16_f32 v21, v24, v21
	global_store_dwordx4 v[22:23], v[18:21], off sc1
	s_nop 1
	v_mul_f32_e32 v20, 0xbfb8aa3b, v14
	v_exp_f32_e32 v20, v20
	v_add_u32_e32 v18, 0xb0, v146
	v_mad_i64_i32 v[18:19], s[4:5], v18, s56, v[140:141]
	v_add_f32_e32 v20, 1.0, v20
	v_rcp_f32_e32 v20, v20
	s_nop 0
	v_mul_f32_e32 v14, v14, v20
	v_mul_f32_e32 v10, v14, v10
	v_mul_f32_e32 v14, 0xbfb8aa3b, v15
	v_exp_f32_e32 v14, v14
	s_nop 0
	v_add_f32_e32 v14, 1.0, v14
	v_rcp_f32_e32 v14, v14
	s_nop 0
	v_mul_f32_e32 v14, v15, v14
	v_mul_f32_e32 v11, v14, v11
	v_mul_f32_e32 v14, 0xbfb8aa3b, v16
	v_exp_f32_e32 v14, v14
	s_nop 0
	v_add_f32_e32 v14, 1.0, v14
	v_rcp_f32_e32 v14, v14
	s_nop 0
	v_mul_f32_e32 v14, v16, v14
	v_mul_f32_e32 v12, v14, v12
	v_mul_f32_e32 v14, 0xbfb8aa3b, v17
	v_exp_f32_e32 v14, v14
	s_nop 0
	v_add_f32_e32 v14, 1.0, v14
	v_rcp_f32_e32 v14, v14
	s_nop 0
	v_mul_f32_e32 v14, v17, v14
	v_mul_f32_e32 v13, v14, v13
	v_mul_f32_e32 v14, 0xbfb8aa3b, v6
	v_exp_f32_e32 v14, v14
	s_nop 0
	v_add_f32_e32 v14, 1.0, v14
	v_rcp_f32_e32 v14, v14
	s_nop 0
	v_mul_f32_e32 v6, v6, v14
	v_mul_f32_e32 v14, v6, v2
	v_mul_f32_e32 v2, 0xbfb8aa3b, v7
	v_exp_f32_e32 v2, v2
	s_nop 0
	v_add_f32_e32 v2, 1.0, v2
	v_rcp_f32_e32 v2, v2
	s_nop 0
	v_mul_f32_e32 v2, v7, v2
	v_mul_f32_e32 v15, v2, v3
	v_mul_f32_e32 v2, 0xbfb8aa3b, v8
	v_exp_f32_e32 v2, v2
	v_lshl_add_u64 v[6:7], v[18:19], 0, v[114:115]
	v_add_f32_e32 v2, 1.0, v2
	v_rcp_f32_e32 v2, v2
	s_nop 0
	v_mul_f32_e32 v2, v8, v2
	v_mul_f32_e32 v8, v2, v4
	v_mul_f32_e32 v2, 0xbfb8aa3b, v9
	v_exp_f32_e32 v2, v2
	s_nop 0
	v_add_f32_e32 v2, 1.0, v2
	v_rcp_f32_e32 v2, v2
	s_nop 0
	v_mul_f32_e32 v2, v9, v2
	v_mul_f32_e32 v5, v2, v5
	v_cvt_pk_bf16_f32 v2, v10, v11
	v_cvt_pk_bf16_f32 v3, v12, v13
	v_cvt_pk_bf16_f32 v4, v14, v15
	v_cvt_pk_bf16_f32 v5, v8, v5
	global_store_dwordx4 v[6:7], v[2:5], off sc1
	s_cbranch_vccnz .LBB0_192
	s_andn2_b64 vcc, exec, s[42:43]
	s_cbranch_vccnz .LBB0_191
	s_barrier
	s_branch .LBB0_191

;     __device__ __forceinline__ void operator()(const f32x4 (&acc)[2][2][4][2], const Unit& u, int wr, int wc, int fr, int fq) const {
;         const int pt = phys_tile(u.pm, skipctx), b = pt / 17, t = pt - b * 17, v = (t == 0) ? 4 : b;
;         const float* inb = in_split ? (t == 0 ? ctxin + (size_t)b * CTXL * DM : xin + ((size_t)b * SEQ + (size_t)(t - 1) * 256) * DM) : xr_in + (size_t)pt * BM * DM;
;         float* ob = out_final ? fin_out + ((size_t)b * SEQ + (size_t)(t - 1) * 256) * DM : xr_out + (size_t)pt * BM * DM;
;         const int col0 = u.pn * BM + wc * 32 + 4 * fq;
;         const float* gp = gate + (size_t)v * 12288 + col0;
;         f32x4 gv[2][2];
; #pragma unroll
;         for (int bj = 0; bj < 2; ++bj)
; #pragma unroll
;             for (int n = 0; n < 2; ++n) gv[bj][n] = *(const f32x4*)(gp + bj * HALF + n * 16);
; #pragma unroll
;         for (int ai = 0; ai < 2; ++ai)
; #pragma unroll
;             for (int m = 0; m < 4; ++m) { const size_t off = (size_t)(ai * HALF + wr * 64 + m * 16 + fr) * DM + col0;
; #pragma unroll
;                 for (int bj = 0; bj < 2; ++bj)
; #pragma unroll
;                     for (int n = 0; n < 2; ++n) { const f32x4 bs = *(const f32x4*)(inb + off + bj * HALF + n * 16);
;                         *(f32x4*)(ob + off + bj * HALF + n * 16) = bs + gv[bj][n] * acc[ai][bj][m][n]; }
;                 if (m == 3) asm volatile("" ::: "memory"); }
;     }
.LBB0_230:
	s_ashr_i32 s14, s56, 4
	s_add_i32 s14, s56, s14
	s_add_i32 s56, s14, 1
	s_mul_hi_i32 s14, s56, 0x78787879
	s_lshr_b32 s15, s14, 31
	s_ashr_i32 s14, s14, 3
	s_add_i32 s14, s14, s15
	s_mul_i32 s15, s14, 0xffffffef
	s_add_i32 s54, s15, s56
	s_ashr_i32 s15, s14, 31
	s_lshl_b64 s[30:31], s[14:15], 25
	s_add_u32 s15, s22, s30
	s_addc_u32 s57, s23, s31
	v_sub_co_u32_e64 v134, vcc, s54, 1
	v_mov_b32_e32 v130, s14
	s_and_b64 s[54:55], vcc, exec
	v_cndmask_b32_e32 v130, v134, v130, vcc
	s_cselect_b32 s15, s46, s15
	s_cselect_b32 s57, s47, s57
	v_mov_b32_e32 v135, s56
	s_and_b64 s[54:55], s[38:39], exec
	v_cndmask_b32_e64 v130, v130, v135, s[38:39]
	s_cselect_b32 s55, s94, s57
	s_cselect_b32 s54, s93, s15
	s_add_u32 s15, s12, s30
	s_addc_u32 s56, s13, s31
	v_ashrrev_i32_e32 v131, 31, v130
	s_and_b64 s[30:31], s[40:41], exec
	v_lshlrev_b64 v[130:131], 21, v[130:131]
	s_cselect_b32 s31, s94, s56
	s_cselect_b32 s30, s93, s15
	v_lshl_add_u64 v[168:169], s[54:55], 0, v[130:131]
	s_and_b64 s[54:55], vcc, exec
	v_lshl_or_b32 v170, s11, 8, v175
	s_cselect_b32 s14, 4, s14
	v_ashrrev_i32_e32 v171, 31, v170
	s_mul_hi_i32 s11, s14, 0xc000
	s_mul_i32 s14, s14, 0xc000
	s_add_u32 s14, s95, s14
	s_addc_u32 s15, s96, s11
	v_cndmask_b32_e64 v134, v134, v135, s[40:41]
	v_ashrrev_i32_e32 v135, 31, v134
	v_lshlrev_b64 v[134:135], 21, v[134:135]
	v_lshl_add_u64 v[172:173], s[30:31], 0, v[134:135]
	v_lshl_add_u64 v[130:131], v[170:171], 2, s[14:15]
	s_and_b64 vcc, exec, s[42:43]
	global_load_dwordx4 v[142:145], v[130:131], off
	global_load_dwordx4 v[138:141], v[130:131], off offset:64
	global_load_dwordx4 v[134:137], v[130:131], off offset:512
	global_load_dwordx4 v[130:133], v[130:131], off offset:576
	s_mov_b64 s[14:15], -1
	v_lshl_add_u64 v[246:247], v[148:149], 0, v[170:171]
	v_lshlrev_b64 v[246:247], 2, v[246:247]
	v_lshl_add_u64 v[198:199], v[172:173], 0, v[246:247]
	v_lshl_add_u64 v[246:247], v[168:169], 0, v[246:247]
	global_load_dwordx4 v[178:181], v[246:247], off
	global_load_dwordx4 v[182:185], v[246:247], off offset:64
	global_load_dwordx4 v[186:189], v[246:247], off offset:512
	global_load_dwordx4 v[190:193], v[246:247], off offset:576
	v_lshl_add_u64 v[246:247], v[150:151], 0, v[170:171]
	v_lshlrev_b64 v[246:247], 2, v[246:247]
	v_lshl_add_u64 v[214:215], v[172:173], 0, v[246:247]
	v_lshl_add_u64 v[246:247], v[168:169], 0, v[246:247]
	global_load_dwordx4 v[194:197], v[246:247], off
	global_load_dwordx4 v[202:205], v[246:247], off offset:64
	global_load_dwordx4 v[206:209], v[246:247], off offset:512
	global_load_dwordx4 v[210:213], v[246:247], off offset:576
	v_lshl_add_u64 v[246:247], v[152:153], 0, v[170:171]
	v_lshlrev_b64 v[246:247], 2, v[246:247]
	v_lshl_add_u64 v[244:245], v[172:173], 0, v[246:247]
	v_lshl_add_u64 v[246:247], v[168:169], 0, v[246:247]
	global_load_dwordx4 v[228:231], v[246:247], off
	global_load_dwordx4 v[232:235], v[246:247], off offset:64
	global_load_dwordx4 v[236:239], v[246:247], off offset:512
	global_load_dwordx4 v[240:243], v[246:247], off offset:576
	s_waitcnt vmcnt(8)
	v_pk_fma_f32 v[128:129], v[128:129], v[144:145], v[180:181]
	v_pk_fma_f32 v[126:127], v[126:127], v[142:143], v[178:179]
	v_pk_fma_f32 v[124:125], v[124:125], v[140:141], v[184:185]
	v_pk_fma_f32 v[122:123], v[122:123], v[138:139], v[182:183]
	v_pk_fma_f32 v[120:121], v[120:121], v[136:137], v[188:189]
	v_pk_fma_f32 v[118:119], v[118:119], v[134:135], v[186:187]
	v_pk_fma_f32 v[108:109], v[108:109], v[132:133], v[192:193]
	v_pk_fma_f32 v[106:107], v[106:107], v[130:131], v[190:191]
	global_store_dwordx4 v[198:199], v[126:129], off sc1
	global_store_dwordx4 v[198:199], v[122:125], off offset:64 sc1
	global_store_dwordx4 v[198:199], v[118:121], off offset:512 sc1
	global_store_dwordx4 v[198:199], v[106:109], off offset:576 sc1
	v_lshl_add_u64 v[246:247], v[154:155], 0, v[170:171]
	v_lshlrev_b64 v[246:247], 2, v[246:247]
	v_lshl_add_u64 v[198:199], v[172:173], 0, v[246:247]
	v_lshl_add_u64 v[246:247], v[168:169], 0, v[246:247]
	global_load_dwordx4 v[178:181], v[246:247], off
	global_load_dwordx4 v[182:185], v[246:247], off offset:64
	global_load_dwordx4 v[186:189], v[246:247], off offset:512
	global_load_dwordx4 v[190:193], v[246:247], off offset:576
	s_waitcnt vmcnt(12)
	v_pk_fma_f32 v[116:117], v[116:117], v[144:145], v[196:197]
	v_pk_fma_f32 v[114:115], v[114:115], v[142:143], v[194:195]
	v_pk_fma_f32 v[112:113], v[112:113], v[140:141], v[204:205]
	v_pk_fma_f32 v[110:111], v[110:111], v[138:139], v[202:203]
	v_pk_fma_f32 v[104:105], v[104:105], v[136:137], v[208:209]
	v_pk_fma_f32 v[102:103], v[102:103], v[134:135], v[206:207]
	v_pk_fma_f32 v[92:93], v[92:93], v[132:133], v[212:213]
	v_pk_fma_f32 v[90:91], v[90:91], v[130:131], v[210:211]
	global_store_dwordx4 v[214:215], v[114:117], off sc1
	global_store_dwordx4 v[214:215], v[110:113], off offset:64 sc1
	global_store_dwordx4 v[214:215], v[102:105], off offset:512 sc1
	global_store_dwordx4 v[214:215], v[90:93], off offset:576 sc1
	v_lshl_add_u64 v[246:247], v[156:157], 0, v[170:171]
	v_lshlrev_b64 v[246:247], 2, v[246:247]
	v_lshl_add_u64 v[214:215], v[172:173], 0, v[246:247]
	v_lshl_add_u64 v[246:247], v[168:169], 0, v[246:247]
	global_load_dwordx4 v[194:197], v[246:247], off
	global_load_dwordx4 v[202:205], v[246:247], off offset:64
	global_load_dwordx4 v[206:209], v[246:247], off offset:512
	global_load_dwordx4 v[210:213], v[246:247], off offset:576
	s_waitcnt vmcnt(16)
;     __device__ __forceinline__ void operator()(const f32x4 (&acc)[2][2][4][2], const Unit& u, int wr, int wc, int fr, int fq) const {
;         const int pt = phys_tile(u.pm, skipctx), b = pt / 17, t = pt - b * 17, v = (t == 0) ? 4 : b;
;         const float* inb = in_split ? (t == 0 ? ctxin + (size_t)b * CTXL * DM : xin + ((size_t)b * SEQ + (size_t)(t - 1) * 256) * DM) : xr_in + (size_t)pt * BM * DM;
;         float* ob = out_final ? fin_out + ((size_t)b * SEQ + (size_t)(t - 1) * 256) * DM : xr_out + (size_t)pt * BM * DM;
;         const int col0 = u.pn * BM + wc * 32 + 4 * fq;
;         const float* gp = gate + (size_t)v * 12288 + col0;
;         f32x4 gv[2][2];
; #pragma unroll
;         for (int bj = 0; bj < 2; ++bj)
; #pragma unroll
;             for (int n = 0; n < 2; ++n) gv[bj][n] = *(const f32x4*)(gp + bj * HALF + n * 16);
; #pragma unroll
;         for (int ai = 0; ai < 2; ++ai)
; #pragma unroll
;             for (int m = 0; m < 4; ++m) { const size_t off = (size_t)(ai * HALF + wr * 64 + m * 16 + fr) * DM + col0;
; #pragma unroll
;                 for (int bj = 0; bj < 2; ++bj)
; #pragma unroll
;                     for (int n = 0; n < 2; ++n) { const f32x4 bs = *(const f32x4*)(inb + off + bj * HALF + n * 16);
;                         *(f32x4*)(ob + off + bj * HALF + n * 16) = bs + gv[bj][n] * acc[ai][bj][m][n]; }
;                 if (m == 3) asm volatile("" ::: "memory"); }
;     }
	v_pk_fma_f32 v[100:101], v[100:101], v[144:145], v[230:231]
	v_pk_fma_f32 v[98:99], v[98:99], v[142:143], v[228:229]
	v_pk_fma_f32 v[96:97], v[96:97], v[140:141], v[234:235]
	v_pk_fma_f32 v[94:95], v[94:95], v[138:139], v[232:233]
	v_pk_fma_f32 v[88:89], v[88:89], v[136:137], v[238:239]
	v_pk_fma_f32 v[86:87], v[86:87], v[134:135], v[236:237]
	v_pk_fma_f32 v[76:77], v[76:77], v[132:133], v[242:243]
	v_pk_fma_f32 v[74:75], v[74:75], v[130:131], v[240:241]
	global_store_dwordx4 v[244:245], v[98:101], off sc1
	global_store_dwordx4 v[244:245], v[94:97], off offset:64 sc1
	global_store_dwordx4 v[244:245], v[86:89], off offset:512 sc1
	global_store_dwordx4 v[244:245], v[74:77], off offset:576 sc1
	v_lshl_add_u64 v[246:247], v[158:159], 0, v[170:171]
	v_lshlrev_b64 v[246:247], 2, v[246:247]
	v_lshl_add_u64 v[244:245], v[172:173], 0, v[246:247]
	v_lshl_add_u64 v[246:247], v[168:169], 0, v[246:247]
	global_load_dwordx4 v[228:231], v[246:247], off
	global_load_dwordx4 v[232:235], v[246:247], off offset:64
	global_load_dwordx4 v[236:239], v[246:247], off offset:512
	global_load_dwordx4 v[240:243], v[246:247], off offset:576
	s_waitcnt vmcnt(16)
	v_pk_fma_f32 v[84:85], v[84:85], v[144:145], v[180:181]
	v_pk_fma_f32 v[82:83], v[82:83], v[142:143], v[178:179]
	v_pk_fma_f32 v[80:81], v[80:81], v[140:141], v[184:185]
	v_pk_fma_f32 v[78:79], v[78:79], v[138:139], v[182:183]
	v_pk_fma_f32 v[72:73], v[72:73], v[136:137], v[188:189]
	v_pk_fma_f32 v[70:71], v[70:71], v[134:135], v[186:187]
	v_pk_fma_f32 v[68:69], v[68:69], v[132:133], v[192:193]
	v_pk_fma_f32 v[66:67], v[66:67], v[130:131], v[190:191]
	global_store_dwordx4 v[198:199], v[82:85], off sc1
	global_store_dwordx4 v[198:199], v[78:81], off offset:64 sc1
	global_store_dwordx4 v[198:199], v[70:73], off offset:512 sc1
	global_store_dwordx4 v[198:199], v[66:69], off offset:576 sc1
	v_lshl_add_u64 v[246:247], v[160:161], 0, v[170:171]
	v_lshlrev_b64 v[246:247], 2, v[246:247]
	v_lshl_add_u64 v[198:199], v[172:173], 0, v[246:247]
	v_lshl_add_u64 v[246:247], v[168:169], 0, v[246:247]
	global_load_dwordx4 v[178:181], v[246:247], off
	global_load_dwordx4 v[182:185], v[246:247], off offset:64
	global_load_dwordx4 v[186:189], v[246:247], off offset:512
	global_load_dwordx4 v[190:193], v[246:247], off offset:576
	s_waitcnt vmcnt(16)
	v_pk_fma_f32 v[64:65], v[64:65], v[144:145], v[196:197]
	v_pk_fma_f32 v[62:63], v[62:63], v[142:143], v[194:195]
	v_pk_fma_f32 v[60:61], v[60:61], v[140:141], v[204:205]
	v_pk_fma_f32 v[58:59], v[58:59], v[138:139], v[202:203]
	v_pk_fma_f32 v[56:57], v[56:57], v[136:137], v[208:209]
	v_pk_fma_f32 v[54:55], v[54:55], v[134:135], v[206:207]
	v_pk_fma_f32 v[44:45], v[44:45], v[132:133], v[212:213]
	v_pk_fma_f32 v[42:43], v[42:43], v[130:131], v[210:211]
	global_store_dwordx4 v[214:215], v[62:65], off sc1
	global_store_dwordx4 v[214:215], v[58:61], off offset:64 sc1
	global_store_dwordx4 v[214:215], v[54:57], off offset:512 sc1
	global_store_dwordx4 v[214:215], v[42:45], off offset:576 sc1
	v_lshl_add_u64 v[246:247], v[162:163], 0, v[170:171]
	v_lshlrev_b64 v[246:247], 2, v[246:247]
	v_lshl_add_u64 v[214:215], v[172:173], 0, v[246:247]
	v_lshl_add_u64 v[246:247], v[168:169], 0, v[246:247]
	global_load_dwordx4 v[194:197], v[246:247], off
	global_load_dwordx4 v[202:205], v[246:247], off offset:64
	global_load_dwordx4 v[206:209], v[246:247], off offset:512
	global_load_dwordx4 v[210:213], v[246:247], off offset:576
	s_waitcnt vmcnt(16)
	v_pk_fma_f32 v[52:53], v[52:53], v[144:145], v[230:231]
	v_pk_fma_f32 v[50:51], v[50:51], v[142:143], v[228:229]
	v_pk_fma_f32 v[48:49], v[48:49], v[140:141], v[234:235]
	v_pk_fma_f32 v[46:47], v[46:47], v[138:139], v[232:233]
	v_pk_fma_f32 v[40:41], v[40:41], v[136:137], v[238:239]
	v_pk_fma_f32 v[38:39], v[38:39], v[134:135], v[236:237]
	v_pk_fma_f32 v[28:29], v[28:29], v[132:133], v[242:243]
	v_pk_fma_f32 v[26:27], v[26:27], v[130:131], v[240:241]
	global_store_dwordx4 v[244:245], v[50:53], off sc1
	global_store_dwordx4 v[244:245], v[46:49], off offset:64 sc1
	global_store_dwordx4 v[244:245], v[38:41], off offset:512 sc1
	global_store_dwordx4 v[244:245], v[26:29], off offset:576 sc1
	s_waitcnt vmcnt(12)
	v_pk_fma_f32 v[36:37], v[36:37], v[144:145], v[180:181]
	v_pk_fma_f32 v[34:35], v[34:35], v[142:143], v[178:179]
	v_pk_fma_f32 v[32:33], v[32:33], v[140:141], v[184:185]
	v_pk_fma_f32 v[30:31], v[30:31], v[138:139], v[182:183]
	v_pk_fma_f32 v[24:25], v[24:25], v[136:137], v[188:189]
	v_pk_fma_f32 v[22:23], v[22:23], v[134:135], v[186:187]
	v_pk_fma_f32 v[12:13], v[12:13], v[132:133], v[192:193]
	v_pk_fma_f32 v[10:11], v[10:11], v[130:131], v[190:191]
	global_store_dwordx4 v[198:199], v[34:37], off sc1
	global_store_dwordx4 v[198:199], v[30:33], off offset:64 sc1
	global_store_dwordx4 v[198:199], v[22:25], off offset:512 sc1
	global_store_dwordx4 v[198:199], v[10:13], off offset:576 sc1
	s_waitcnt vmcnt(8)
	v_pk_fma_f32 v[20:21], v[20:21], v[144:145], v[196:197]
	v_pk_fma_f32 v[18:19], v[18:19], v[142:143], v[194:195]
	v_pk_fma_f32 v[16:17], v[16:17], v[140:141], v[204:205]
	v_pk_fma_f32 v[14:15], v[14:15], v[138:139], v[202:203]
	v_pk_fma_f32 v[8:9], v[8:9], v[136:137], v[208:209]
	v_pk_fma_f32 v[6:7], v[6:7], v[134:135], v[206:207]
	v_pk_fma_f32 v[4:5], v[4:5], v[132:133], v[212:213]
	v_pk_fma_f32 v[2:3], v[2:3], v[130:131], v[210:211]
	global_store_dwordx4 v[214:215], v[18:21], off sc1
	global_store_dwordx4 v[214:215], v[14:17], off offset:64 sc1
	global_store_dwordx4 v[214:215], v[6:9], off offset:512 sc1
	global_store_dwordx4 v[214:215], v[2:5], off offset:576 sc1
	s_cbranch_vccnz .LBB0_215
	s_andn2_b64 vcc, exec, s[48:49]
	s_cbranch_vccnz .LBB0_214
	s_barrier
	s_branch .LBB0_214

;     __device__ __forceinline__ void operator()(const f32x4 (&acc)[2][2][4][2], const Unit& u, int wr, int wc, int fr, int fq) const {
;         float* t = P + ((size_t)(u.kp * 32 + u.pm * 8 + u.pn) << 16); const int col0 = wc * 32 + 4 * fq;
; #pragma unroll
;         for (int ai = 0; ai < 2; ++ai)
; #pragma unroll
;             for (int m = 0; m < 4; ++m) { float* rp = t + (ai * HALF + wr * 64 + m * 16 + fr) * 256 + col0;
; #pragma unroll
;                 for (int bj = 0; bj < 2; ++bj)
; #pragma unroll
;                     for (int n = 0; n < 2; ++n) *(f32x4*)(rp + bj * HALF + n * 16) = acc[ai][bj][m][n]; }
;     }
.LBB0_259:
	s_lshl_b32 s6, s6, 5
	s_lshl_b32 s15, s15, 3
	s_add_i32 s6, s14, s6
	s_add_i32 s14, s6, s15
	s_ashr_i32 s15, s14, 31
	s_lshl_b64 s[14:15], s[14:15], 18
	v_lshl_add_u64 v[150:151], v[132:133], 0, s[14:15]
	v_lshl_add_u64 v[152:153], v[134:135], 2, v[150:151]
	global_store_dwordx4 v[152:153], v[126:129], off sc1
	global_store_dwordx4 v[152:153], v[122:125], off offset:64 sc1
	global_store_dwordx4 v[152:153], v[110:113], off offset:512 sc1
	global_store_dwordx4 v[152:153], v[102:105], off offset:576 sc1
	s_mov_b32 s6, 0x8000
	s_mov_b64 s[14:15], -1
	v_add_co_u32_e32 v102, vcc, 0x4000, v152
	s_nop 1
	v_addc_co_u32_e32 v103, vcc, 0, v153, vcc
	global_store_dwordx4 v[102:103], v[118:121], off sc1
	global_store_dwordx4 v[102:103], v[114:117], off offset:64 sc1
	global_store_dwordx4 v[102:103], v[94:97], off offset:512 sc1
	global_store_dwordx4 v[102:103], v[86:89], off offset:576 sc1
	s_nop 1
	v_add_co_u32_e32 v86, vcc, s6, v152
	s_nop 1
	v_addc_co_u32_e32 v87, vcc, 0, v153, vcc
	global_store_dwordx4 v[86:87], v[106:109], off sc1
	global_store_dwordx4 v[86:87], v[98:101], off offset:64 sc1
	global_store_dwordx4 v[86:87], v[78:81], off offset:512 sc1
	global_store_dwordx4 v[86:87], v[74:77], off offset:576 sc1
	s_nop 1
	v_add_co_u32_e32 v74, vcc, s81, v152
	s_nop 1
	v_addc_co_u32_e32 v75, vcc, 0, v153, vcc
	global_store_dwordx4 v[74:75], v[90:93], off sc1
	global_store_dwordx4 v[74:75], v[82:85], off offset:64 sc1
	global_store_dwordx4 v[74:75], v[70:73], off offset:512 sc1
	global_store_dwordx4 v[74:75], v[66:69], off offset:576 sc1
	s_and_b64 vcc, exec, s[38:39]
	s_nop 0
	v_lshl_add_u64 v[66:67], v[136:137], 2, v[150:151]
	global_store_dwordx4 v[66:67], v[62:65], off sc1
	global_store_dwordx4 v[66:67], v[58:61], off offset:64 sc1
	global_store_dwordx4 v[66:67], v[38:41], off offset:512 sc1
	global_store_dwordx4 v[66:67], v[30:33], off offset:576 sc1
	s_nop 1
	v_lshl_add_u64 v[30:31], v[138:139], 2, v[150:151]
	global_store_dwordx4 v[30:31], v[54:57], off sc1
	global_store_dwordx4 v[30:31], v[50:53], off offset:64 sc1
	global_store_dwordx4 v[30:31], v[22:25], off offset:512 sc1
	global_store_dwordx4 v[30:31], v[18:21], off offset:576 sc1
	s_nop 1
	v_lshl_add_u64 v[18:19], v[140:141], 2, v[150:151]
	global_store_dwordx4 v[18:19], v[46:49], off sc1
	global_store_dwordx4 v[18:19], v[42:45], off offset:64 sc1
	global_store_dwordx4 v[18:19], v[14:17], off offset:512 sc1
	global_store_dwordx4 v[18:19], v[10:13], off offset:576 sc1
	s_nop 1
	v_lshl_add_u64 v[10:11], v[142:143], 2, v[150:151]
	global_store_dwordx4 v[10:11], v[34:37], off sc1
	global_store_dwordx4 v[10:11], v[26:29], off offset:64 sc1
	global_store_dwordx4 v[10:11], v[6:9], off offset:512 sc1
	global_store_dwordx4 v[10:11], v[2:5], off offset:576 sc1
	s_cbranch_vccnz .LBB0_244
	s_andn2_b64 vcc, exec, s[22:23]
	s_cbranch_vccnz .LBB0_243
	s_barrier
	s_branch .LBB0_243

; __device__ __forceinline__ unsigned cvt_pk_bf16(float lo, float hi) { unsigned r; asm volatile("v_cvt_pk_bf16_f32 %0, %1, %2" : "=v"(r) : "v"(lo), "v"(hi)); return r; }
;     __device__ __forceinline__ void operator()(const f32x4 (&acc)[2][2][4][2], const Unit& u, int wr, int wc, int fr, int fq) const {
;         const int row0 = phys_tile(u.pm, skipctx) * BM + wr * 64 + fr, col0 = u.pn * BM + wc * 32 + 8 * fq;
; #pragma unroll
;         for (int ai = 0; ai < 2; ++ai)
; #pragma unroll
;             for (int m = 0; m < 4; ++m) { bf16_t* rowp = O + (size_t)(row0 + ai * HALF + m * 16) * ldc + col0;
; #pragma unroll
;                 for (int bj = 0; bj < 2; ++bj) { const f32x4 v0 = acc[ai][bj][m][0], v1 = acc[ai][bj][m][1];
;                     u32x4 w; w.x = cvt_pk_bf16(v0[0], v0[1]); w.y = cvt_pk_bf16(v0[2], v0[3]); w.z = cvt_pk_bf16(v1[0], v1[1]); w.w = cvt_pk_bf16(v1[2], v1[3]);
;                     *(u32x4*)(rowp + bj * HALF) = w; } }
;     }
.LBB0_295:
	v_lshl_or_b32 v140, s57, 8, v144
	v_lshl_add_u32 v148, s58, 8, v142
	v_ashrrev_i32_e32 v141, 31, v140
	v_mad_i64_i32 v[146:147], s[14:15], v148, s35, 0
	v_lshl_add_u64 v[146:147], v[146:147], 1, s[42:43]
	v_lshlrev_b64 v[140:141], 1, v[140:141]
	v_lshl_add_u64 v[146:147], v[146:147], 0, v[140:141]
	v_cvt_pk_bf16_f32 v126, v126, v127
	v_cvt_pk_bf16_f32 v127, v128, v129
	v_cvt_pk_bf16_f32 v128, v122, v123
	v_cvt_pk_bf16_f32 v129, v124, v125
	global_store_dwordx4 v[146:147], v[126:129], off sc1
	v_cvt_pk_bf16_f32 v114, v114, v115
	v_cvt_pk_bf16_f32 v115, v116, v117
	v_cvt_pk_bf16_f32 v116, v106, v107
	v_or_b32_e32 v106, 16, v148
	v_mad_i64_i32 v[106:107], s[14:15], v106, s35, 0
	v_lshl_add_u64 v[106:107], v[106:107], 1, s[42:43]
	v_cvt_pk_bf16_f32 v117, v108, v109
	global_store_dwordx4 v[146:147], v[114:117], off offset:256 sc1
	s_and_b64 vcc, exec, s[38:39]
	s_nop 0
	v_lshl_add_u64 v[114:115], v[106:107], 0, v[140:141]
	v_cvt_pk_bf16_f32 v106, v118, v119
	v_cvt_pk_bf16_f32 v107, v120, v121
	v_cvt_pk_bf16_f32 v108, v110, v111
	v_cvt_pk_bf16_f32 v109, v112, v113
	global_store_dwordx4 v[114:115], v[106:109], off sc1
	v_cvt_pk_bf16_f32 v98, v98, v99
	v_cvt_pk_bf16_f32 v99, v100, v101
	v_cvt_pk_bf16_f32 v100, v90, v91
	v_or_b32_e32 v90, 32, v148
	v_mad_i64_i32 v[90:91], s[14:15], v90, s35, 0
	v_lshl_add_u64 v[90:91], v[90:91], 1, s[42:43]
	v_cvt_pk_bf16_f32 v101, v92, v93
	global_store_dwordx4 v[114:115], v[98:101], off offset:256 sc1
	s_nop 1
	v_lshl_add_u64 v[98:99], v[90:91], 0, v[140:141]
	v_cvt_pk_bf16_f32 v90, v102, v103
	v_cvt_pk_bf16_f32 v91, v104, v105
	v_cvt_pk_bf16_f32 v92, v94, v95
	v_cvt_pk_bf16_f32 v93, v96, v97
	global_store_dwordx4 v[98:99], v[90:93], off sc1
	v_cvt_pk_bf16_f32 v82, v82, v83
	v_cvt_pk_bf16_f32 v83, v84, v85
	v_cvt_pk_bf16_f32 v84, v74, v75
	v_or_b32_e32 v74, 48, v148
	v_mad_i64_i32 v[74:75], s[14:15], v74, s35, 0
	v_lshl_add_u64 v[74:75], v[74:75], 1, s[42:43]
	v_cvt_pk_bf16_f32 v85, v76, v77
	global_store_dwordx4 v[98:99], v[82:85], off offset:256 sc1
	s_nop 1
	v_lshl_add_u64 v[82:83], v[74:75], 0, v[140:141]
	v_cvt_pk_bf16_f32 v74, v86, v87
	v_cvt_pk_bf16_f32 v75, v88, v89
	v_cvt_pk_bf16_f32 v76, v78, v79
	v_cvt_pk_bf16_f32 v77, v80, v81
	global_store_dwordx4 v[82:83], v[74:77], off sc1
	v_cvt_pk_bf16_f32 v70, v70, v71
	v_cvt_pk_bf16_f32 v71, v72, v73
	v_cvt_pk_bf16_f32 v72, v66, v67
	v_add_u32_e32 v66, 0x80, v148
	v_mad_i64_i32 v[66:67], s[14:15], v66, s35, 0
	v_lshl_add_u64 v[66:67], v[66:67], 1, s[42:43]
	v_lshl_add_u64 v[66:67], v[66:67], 0, v[140:141]
	v_cvt_pk_bf16_f32 v73, v68, v69
	global_store_dwordx4 v[82:83], v[70:73], off offset:256 sc1
	v_cvt_pk_bf16_f32 v62, v62, v63
	v_cvt_pk_bf16_f32 v63, v64, v65
	v_cvt_pk_bf16_f32 v64, v58, v59
	v_cvt_pk_bf16_f32 v65, v60, v61
	global_store_dwordx4 v[66:67], v[62:65], off sc1
	v_cvt_pk_bf16_f32 v50, v50, v51
	v_cvt_pk_bf16_f32 v51, v52, v53
	v_cvt_pk_bf16_f32 v52, v42, v43
	v_add_u32_e32 v42, 0x90, v148
	v_mad_i64_i32 v[42:43], s[14:15], v42, s35, 0
	v_lshl_add_u64 v[42:43], v[42:43], 1, s[42:43]
	v_cvt_pk_bf16_f32 v53, v44, v45
	global_store_dwordx4 v[66:67], v[50:53], off offset:256 sc1
	s_nop 1
	v_lshl_add_u64 v[50:51], v[42:43], 0, v[140:141]
	v_cvt_pk_bf16_f32 v42, v54, v55
	v_cvt_pk_bf16_f32 v43, v56, v57
	v_cvt_pk_bf16_f32 v44, v46, v47
	v_cvt_pk_bf16_f32 v45, v48, v49
	global_store_dwordx4 v[50:51], v[42:45], off sc1
	v_cvt_pk_bf16_f32 v34, v34, v35
	v_cvt_pk_bf16_f32 v35, v36, v37
	v_cvt_pk_bf16_f32 v36, v26, v27
	v_add_u32_e32 v26, 0xa0, v148
	v_mad_i64_i32 v[26:27], s[14:15], v26, s35, 0
	v_lshl_add_u64 v[26:27], v[26:27], 1, s[42:43]
	v_cvt_pk_bf16_f32 v37, v28, v29
	global_store_dwordx4 v[50:51], v[34:37], off offset:256 sc1
	s_nop 1
	v_lshl_add_u64 v[34:35], v[26:27], 0, v[140:141]
	v_cvt_pk_bf16_f32 v26, v38, v39
	v_cvt_pk_bf16_f32 v27, v40, v41
	v_cvt_pk_bf16_f32 v28, v30, v31
	v_cvt_pk_bf16_f32 v29, v32, v33
	global_store_dwordx4 v[34:35], v[26:29], off sc1
	v_cvt_pk_bf16_f32 v18, v18, v19
	v_cvt_pk_bf16_f32 v19, v20, v21
	v_cvt_pk_bf16_f32 v20, v10, v11
	v_add_u32_e32 v10, 0xb0, v148
	v_mad_i64_i32 v[10:11], s[14:15], v10, s35, 0
	v_lshl_add_u64 v[10:11], v[10:11], 1, s[42:43]
	v_cvt_pk_bf16_f32 v21, v12, v13
	global_store_dwordx4 v[34:35], v[18:21], off offset:256 sc1
	s_mov_b64 s[14:15], -1
	s_nop 0
	v_lshl_add_u64 v[18:19], v[10:11], 0, v[140:141]
	v_cvt_pk_bf16_f32 v10, v22, v23
	v_cvt_pk_bf16_f32 v11, v24, v25
	v_cvt_pk_bf16_f32 v12, v14, v15
	v_cvt_pk_bf16_f32 v13, v16, v17
	global_store_dwordx4 v[18:19], v[10:13], off sc1
	v_cvt_pk_bf16_f32 v6, v6, v7
	v_cvt_pk_bf16_f32 v7, v8, v9
	v_cvt_pk_bf16_f32 v8, v2, v3
	v_cvt_pk_bf16_f32 v9, v4, v5
	global_store_dwordx4 v[18:19], v[6:9], off offset:256 sc1
	s_cbranch_vccnz .LBB0_280
	s_andn2_b64 vcc, exec, s[50:51]
	s_cbranch_vccnz .LBB0_279
	s_barrier
	s_branch .LBB0_279
